# grid barrier master sweep: the 16 counter polls issued back to back with one wait (same sum), on top of v48
# baseline (speedup 1.0000x reference)
; DI unsigned xb_ld(unsigned* p) { return __hip_atomic_load(p, __ATOMIC_RELAXED, __HIP_MEMORY_SCOPE_AGENT); }
; DI void xcd_barrier_complete(unsigned* bar, unsigned x, unsigned& nloc, unsigned& nx) {
;     ...
;   for (;;) {
;     sum = 0u; cnt = 0u; mine = 0u;
; #pragma unroll
;     for (unsigned j = 0; j < 16; ++j) { const unsigned c = xb_ld(&bar[XB_XCNT(j)]); sum += c; cnt += (c > 0u) ? 1u : 0u; mine = (j == x) ? c : mine; }
;     if (sum == G) break;
;     __builtin_amdgcn_s_sleep(1);
;     if ((++sp & 255u) == 0u) { if (xb_ld(&bar[XB_TMO])) break; if (sp > XB_SPIN_CAP) { atomicAdd(&bar[XB_TMO], 1u); break; } }
;   }
.LBB0_62:
	v_readlane_b32 s4, v253, 10
	v_readlane_b32 s5, v253, 11
	s_mov_b64 s[6:7], -1
	s_nop 3
	global_load_dword v0, v157, s[4:5] sc1
	v_readlane_b32 s4, v253, 12
	v_readlane_b32 s5, v253, 13
	s_nop 4
	global_load_dword v1, v157, s[4:5] sc1
	v_readlane_b32 s4, v253, 14
	v_readlane_b32 s5, v253, 15
	s_nop 4
	global_load_dword v2, v157, s[4:5] sc1
	v_readlane_b32 s4, v253, 16
	v_readlane_b32 s5, v253, 17
	s_nop 4
	global_load_dword v3, v157, s[4:5] sc1
	v_readlane_b32 s4, v253, 18
	v_readlane_b32 s5, v253, 19
	s_nop 4
	global_load_dword v4, v157, s[4:5] sc1
	v_readlane_b32 s4, v253, 20
	v_readlane_b32 s5, v253, 21
	s_nop 4
	global_load_dword v5, v157, s[4:5] sc1
	v_readlane_b32 s4, v253, 22
	v_readlane_b32 s5, v253, 23
	s_nop 4
	global_load_dword v6, v157, s[4:5] sc1
	v_readlane_b32 s4, v253, 24
	v_readlane_b32 s5, v253, 25
	s_nop 4
	global_load_dword v7, v157, s[4:5] sc1
	v_readlane_b32 s4, v253, 26
	v_readlane_b32 s5, v253, 27
	s_nop 4
	global_load_dword v8, v157, s[4:5] sc1
	v_readlane_b32 s4, v253, 28
	v_readlane_b32 s5, v253, 29
	s_nop 4
	global_load_dword v9, v157, s[4:5] sc1
	v_readlane_b32 s4, v253, 30
	v_readlane_b32 s5, v253, 31
	s_nop 4
	global_load_dword v10, v157, s[4:5] sc1
	v_readlane_b32 s4, v253, 32
	v_readlane_b32 s5, v253, 33
	s_nop 4
	global_load_dword v11, v157, s[4:5] sc1
	v_readlane_b32 s4, v253, 34
	v_readlane_b32 s5, v253, 35
	s_nop 4
	global_load_dword v12, v157, s[4:5] sc1
	v_readlane_b32 s4, v253, 36
	v_readlane_b32 s5, v253, 37
	s_nop 4
	global_load_dword v13, v157, s[4:5] sc1
	v_readlane_b32 s4, v253, 38
	v_readlane_b32 s5, v253, 39
	s_nop 4
	global_load_dword v14, v157, s[4:5] sc1
	v_readlane_b32 s4, v253, 40
	v_readlane_b32 s5, v253, 41
	s_nop 4
	global_load_dword v15, v157, s[4:5] sc1
	s_mov_b64 s[4:5], -1
	s_waitcnt vmcnt(0)
	v_add_u32_e32 v16, v1, v0
	v_add_u32_e32 v16, v16, v2
	v_add_u32_e32 v16, v16, v3
	v_add_u32_e32 v16, v16, v4
	v_add_u32_e32 v16, v16, v5
	v_add_u32_e32 v16, v16, v6
	v_add_u32_e32 v16, v16, v7
	v_add_u32_e32 v16, v16, v8
	v_add_u32_e32 v16, v16, v9
	v_add_u32_e32 v16, v16, v10
	v_add_u32_e32 v16, v16, v11
	v_add_u32_e32 v16, v16, v12
	v_add_u32_e32 v16, v16, v13
	v_add_u32_e32 v16, v16, v14
	v_add_u32_e32 v16, v16, v15
	v_cmp_eq_u32_e32 vcc, s12, v16
	s_cbranch_vccnz .LBB0_61
	s_and_b32 s4, s13, 0xff
	s_cmp_eq_u32 s4, 0
	s_mov_b64 s[4:5], -1
	s_mov_b64 s[10:11], -1
	s_sleep 1
	s_cbranch_scc0 .LBB0_66
	v_readlane_b32 s4, v253, 8
	v_readlane_b32 s5, v253, 9
	s_nop 4
	global_load_dword v16, v157, s[4:5] sc1
	s_waitcnt vmcnt(0)
	v_cmp_eq_u32_e32 vcc, 0, v16
	s_cbranch_vccnz .LBB0_68
	s_mov_b64 s[10:11], 0
	s_mov_b64 s[4:5], -1
